# attention: selected + sliding-window branches rewritten by hand (LDS-DMA K/V tiles, reference folded into MFMA C init, no per-block cross-lane max)
# speedup vs baseline: 1.1926x; 1.0537x over previous
.LBB0_165:
	v_lshlrev_b32_e32 v0, 3, v132
	v_and_b32_e32 v0, 0xf8, v0
	s_waitcnt lgkmcnt(0)
	s_barrier
	ds_read_b32 v188, v1 offset:65024
	v_and_b32_e32 v212, 15, v163
	v_bfe_u32 v213, v163, 4, 2
	v_lshrrev_b32_e32 v189, 6, v163
	v_mov_b32_e32 v216, -1
	v_mov_b32_e32 v217, -1
	s_waitcnt lgkmcnt(0)
	v_readfirstlane_b32 s2, v188
	v_readfirstlane_b32 s7, v189
	s_lshr_b32 s3, s2, 3
	s_sub_i32 s3, 0x7f, s3
	s_and_b32 s6, s2, 7
	s_lshr_b32 s4, s3, 1
	s_and_b32 s5, s3, 1
	s_lshl_b32 s5, s5, 5
	s_lshr_b32 s28, s6, 1
	s_lshl_b32 s9, s28, 12
	s_lshl_b32 s29, s3, 5
	s_add_i32 s9, s9, s29
	s_and_b32 s8, s6, 1
	s_lshl_b32 s8, s8, 2
	s_add_i32 s8, s8, s7
	s_lshl_b32 s18, s7, 10
	v_readlane_b32 s52, v236, 41
	v_readlane_b32 s53, v236, 42
	s_lshl_b32 s28, s8, 7
	s_add_u32 s52, s52, s28
	s_addc_u32 s53, s53, 0
	v_add_u32_e32 v190, s9, v212
	v_lshlrev_b32_e32 v191, 10, v190
	v_lshl_add_u32 v191, v213, 4, v191
	v_add_u32_e32 v206, 0x4000, v191
	global_load_dwordx4 v[98:101], v191, s[52:53]
	global_load_dwordx4 v[102:105], v191, s[52:53] offset:64
	global_load_dwordx4 v[106:109], v206, s[52:53]
	global_load_dwordx4 v[110:113], v206, s[52:53] offset:64
	v_readlane_b32 s36, v236, 31
	v_readlane_b32 s37, v236, 32
	s_mul_i32 s28, s8, 6
	s_add_i32 s28, s28, 0x3200
	s_add_u32 s36, s36, s28
	s_addc_u32 s37, s37, 0
	v_mul_u32_u24_e32 v207, 0x3300, v190
	v_add_u32_e32 v208, 0x33000, v207
	global_load_ushort v160, v207, s[36:37] offset:2
	global_load_ushort v182, v207, s[36:37] offset:4
	global_load_ushort v161, v208, s[36:37] offset:2
	global_load_ushort v183, v208, s[36:37] offset:4
	v_readlane_b32 s38, v236, 39
	v_readlane_b32 s39, v236, 40
	s_lshl_b32 s28, s8, 7
	s_add_u32 s38, s38, s28
	s_addc_u32 s39, s39, 0
	v_mul_u32_u24_e32 v184, 0x480, v190
	v_lshl_add_u32 v184, v213, 3, v184
	v_add_u32_e32 v185, 0x4800, v184
	v_lshlrev_b32_e32 v209, 3, v212
	ds_read_b64 v[154:155], v209 offset:24704
	ds_read_b64 v[156:157], v209 offset:24832
	v_lshlrev_b32_e32 v210, 2, v213
	v_sub_u32_e32 v158, v212, v210
	v_add_u32_e32 v158, s5, v158
	v_add_u32_e32 v159, 16, v158
	v_and_b32_e32 v209, 31, v163
	v_lshlrev_b32_e32 v209, 3, v209
	ds_read_b64 v[210:211], v209 offset:24704
	v_bfe_u32 v190, v163, 1, 3
	v_and_b32_e32 v206, 3, v190
	v_xor_b32_e32 v206, v206, v213
	v_lshlrev_b32_e32 v206, 4, v206
	v_lshrrev_b32_e32 v207, 2, v190
	v_lshl_or_b32 v206, v207, 6, v206
	v_lshl_or_b32 v132, v212, 7, v206
	v_xor_b32_e32 v133, 64, v132
	v_lshrrev_b32_e32 v206, 1, v213
	v_and_b32_e32 v207, 1, v190
	v_xor_b32_e32 v206, v206, v207
	v_and_b32_e32 v207, 6, v190
	v_or_b32_e32 v206, v206, v207
	v_lshlrev_b32_e32 v206, 4, v206
	v_and_b32_e32 v207, 1, v213
	v_lshl_or_b32 v206, v207, 3, v206
	v_lshl_or_b32 v134, v212, 7, v206
	v_add_u32_e32 v134, 0x2000, v134
	v_xor_b32_e32 v135, 32, v134
	v_xor_b32_e32 v148, 64, v134
	v_xor_b32_e32 v149, 32, v148
	v_lshrrev_b32_e32 v206, 3, v163
	v_and_b32_e32 v207, 7, v163
	v_bfe_u32 v208, v163, 4, 3
	v_xor_b32_e32 v207, v207, v208
	v_lshlrev_b32_e32 v207, 4, v207
	v_lshl_add_u32 v150, v206, 7, v207
	v_add_u32_e32 v151, 0x1000, v150
	v_mul_u32_u24_e32 v152, 0x2080, v206
	v_add_u32_e32 v152, v152, v207
	v_add_u32_e32 v153, 0x41000, v152
	v_and_b32_e32 v214, 63, v163
	v_xor_b32_e32 v214, 32, v214
	v_lshlrev_b32_e32 v214, 2, v214
	s_waitcnt lgkmcnt(0)
	s_mov_b64 s[20:21], 0
	v_readlane_b32 s28, v210, 0
	v_readlane_b32 s29, v211, 0
	s_or_b64 s[20:21], s[20:21], s[28:29]
	v_readlane_b32 s28, v210, 1
	v_readlane_b32 s29, v211, 1
	s_or_b64 s[20:21], s[20:21], s[28:29]
	v_readlane_b32 s28, v210, 2
	v_readlane_b32 s29, v211, 2
	s_or_b64 s[20:21], s[20:21], s[28:29]
	v_readlane_b32 s28, v210, 3
	v_readlane_b32 s29, v211, 3
	s_or_b64 s[20:21], s[20:21], s[28:29]
	v_readlane_b32 s28, v210, 4
	v_readlane_b32 s29, v211, 4
	s_or_b64 s[20:21], s[20:21], s[28:29]
	v_readlane_b32 s28, v210, 5
	v_readlane_b32 s29, v211, 5
	s_or_b64 s[20:21], s[20:21], s[28:29]
	v_readlane_b32 s28, v210, 6
	v_readlane_b32 s29, v211, 6
	s_or_b64 s[20:21], s[20:21], s[28:29]
	v_readlane_b32 s28, v210, 7
	v_readlane_b32 s29, v211, 7
	s_or_b64 s[20:21], s[20:21], s[28:29]
	v_readlane_b32 s28, v210, 8
	v_readlane_b32 s29, v211, 8
	s_or_b64 s[20:21], s[20:21], s[28:29]
	v_readlane_b32 s28, v210, 9
	v_readlane_b32 s29, v211, 9
	s_or_b64 s[20:21], s[20:21], s[28:29]
	v_readlane_b32 s28, v210, 10
	v_readlane_b32 s29, v211, 10
	s_or_b64 s[20:21], s[20:21], s[28:29]
	v_readlane_b32 s28, v210, 11
	v_readlane_b32 s29, v211, 11
	s_or_b64 s[20:21], s[20:21], s[28:29]
	v_readlane_b32 s28, v210, 12
	v_readlane_b32 s29, v211, 12
	s_or_b64 s[20:21], s[20:21], s[28:29]
	v_readlane_b32 s28, v210, 13
	v_readlane_b32 s29, v211, 13
	s_or_b64 s[20:21], s[20:21], s[28:29]
	v_readlane_b32 s28, v210, 14
	v_readlane_b32 s29, v211, 14
	s_or_b64 s[20:21], s[20:21], s[28:29]
	v_readlane_b32 s28, v210, 15
	v_readlane_b32 s29, v211, 15
	s_or_b64 s[20:21], s[20:21], s[28:29]
	v_readlane_b32 s28, v210, 16
	v_readlane_b32 s29, v211, 16
	s_or_b64 s[20:21], s[20:21], s[28:29]
	v_readlane_b32 s28, v210, 17
	v_readlane_b32 s29, v211, 17
	s_or_b64 s[20:21], s[20:21], s[28:29]
	v_readlane_b32 s28, v210, 18
	v_readlane_b32 s29, v211, 18
	s_or_b64 s[20:21], s[20:21], s[28:29]
	v_readlane_b32 s28, v210, 19
	v_readlane_b32 s29, v211, 19
	s_or_b64 s[20:21], s[20:21], s[28:29]
	v_readlane_b32 s28, v210, 20
	v_readlane_b32 s29, v211, 20
	s_or_b64 s[20:21], s[20:21], s[28:29]
	v_readlane_b32 s28, v210, 21
	v_readlane_b32 s29, v211, 21
	s_or_b64 s[20:21], s[20:21], s[28:29]
	v_readlane_b32 s28, v210, 22
	v_readlane_b32 s29, v211, 22
	s_or_b64 s[20:21], s[20:21], s[28:29]
	v_readlane_b32 s28, v210, 23
	v_readlane_b32 s29, v211, 23
	s_or_b64 s[20:21], s[20:21], s[28:29]
	v_readlane_b32 s28, v210, 24
	v_readlane_b32 s29, v211, 24
	s_or_b64 s[20:21], s[20:21], s[28:29]
	v_readlane_b32 s28, v210, 25
	v_readlane_b32 s29, v211, 25
	s_or_b64 s[20:21], s[20:21], s[28:29]
	v_readlane_b32 s28, v210, 26
	v_readlane_b32 s29, v211, 26
	s_or_b64 s[20:21], s[20:21], s[28:29]
	v_readlane_b32 s28, v210, 27
	v_readlane_b32 s29, v211, 27
	s_or_b64 s[20:21], s[20:21], s[28:29]
	v_readlane_b32 s28, v210, 28
	v_readlane_b32 s29, v211, 28
	s_or_b64 s[20:21], s[20:21], s[28:29]
	v_readlane_b32 s28, v210, 29
	v_readlane_b32 s29, v211, 29
	s_or_b64 s[20:21], s[20:21], s[28:29]
	v_readlane_b32 s28, v210, 30
	v_readlane_b32 s29, v211, 30
	s_or_b64 s[20:21], s[20:21], s[28:29]
	v_readlane_b32 s28, v210, 31
	v_readlane_b32 s29, v211, 31
	s_or_b64 s[20:21], s[20:21], s[28:29]
	v_readlane_b32 s10, v236, 43
	v_readlane_b32 s11, v236, 44
	s_lshl_b32 s28, s6, 19
	s_add_u32 s10, s10, s28
	s_addc_u32 s11, s11, 0
	v_readlane_b32 s12, v237, 51
	v_readlane_b32 s13, v237, 52
	s_mul_i32 s28, s6, 0x82000
	s_add_u32 s12, s12, s28
	s_addc_u32 s13, s13, 0
	s_mov_b32 s27, -1
	s_mov_b32 s26, 0
	s_waitcnt vmcnt(0)
	v_mov_b32_e32 v128, 0
	v_mov_b32_e32 v130, 0
	v_mov_b32_e32 v129, 0
	v_mov_b32_e32 v131, 0
	v_mov_b32_e32 v2, 0
	v_mov_b32_e32 v3, 0
	v_mov_b32_e32 v4, 0
	v_mov_b32_e32 v5, 0
	v_mov_b32_e32 v6, 0
	v_mov_b32_e32 v7, 0
	v_mov_b32_e32 v8, 0
	v_mov_b32_e32 v9, 0
	v_mov_b32_e32 v10, 0
	v_mov_b32_e32 v11, 0
	v_mov_b32_e32 v12, 0
	v_mov_b32_e32 v13, 0
	v_mov_b32_e32 v14, 0
	v_mov_b32_e32 v15, 0
	v_mov_b32_e32 v16, 0
	v_mov_b32_e32 v17, 0
	v_mov_b32_e32 v18, 0
	v_mov_b32_e32 v19, 0
	v_mov_b32_e32 v20, 0
	v_mov_b32_e32 v21, 0
	v_mov_b32_e32 v22, 0
	v_mov_b32_e32 v23, 0
	v_mov_b32_e32 v24, 0
	v_mov_b32_e32 v25, 0
	v_mov_b32_e32 v26, 0
	v_mov_b32_e32 v27, 0
	v_mov_b32_e32 v28, 0
	v_mov_b32_e32 v29, 0
	v_mov_b32_e32 v30, 0
	v_mov_b32_e32 v31, 0
	v_mov_b32_e32 v32, 0
	v_mov_b32_e32 v33, 0
	s_mov_b32 s24, 1
	s_ff1_i32_b64 s22, s[20:21]
	s_add_u32 s28, s20, -1
	s_addc_u32 s29, s21, -1
	s_and_b64 s[20:21], s[20:21], s[28:29]
	s_lshl_b32 s28, s22, 13
	s_add_u32 s14, s10, s28
	s_addc_u32 s15, s11, 0
	s_lshl_b32 s28, s22, 7
	s_add_u32 s16, s12, s28
	s_addc_u32 s17, s13, 0
	s_mov_b32 m0, s18
	s_nop 0
	global_load_lds_dwordx4 v150, s[14:15]
	s_add_u32 m0, s18, 0x1000
	s_nop 0
	global_load_lds_dwordx4 v151, s[14:15]
	s_add_u32 m0, s18, 0x2000
	s_nop 0
	global_load_lds_dwordx4 v152, s[16:17]
	s_add_u32 m0, s18, 0x3000
	s_nop 0
	global_load_lds_dwordx4 v153, s[16:17]
	s_waitcnt vmcnt(0)
	s_barrier
	s_branch .La2_it0
.La2_it0:
	s_cmp_eq_u64 s[20:21], 0
	s_cselect_b32 s25, 1, 0
	s_ff1_i32_b64 s23, s[20:21]
	s_add_u32 s28, s20, -1
	s_addc_u32 s29, s21, -1
	s_and_b64 s[20:21], s[20:21], s[28:29]
	s_cmp_eq_u32 s25, 1
	s_cbranch_scc1 .La2_nodma0
	s_lshl_b32 s28, s23, 13
	s_add_u32 s14, s10, s28
	s_addc_u32 s15, s11, 0
	s_lshl_b32 s28, s23, 7
	s_add_u32 s16, s12, s28
	s_addc_u32 s17, s13, 0
	s_add_u32 m0, s18, 0x8000
	s_nop 0
	global_load_lds_dwordx4 v150, s[14:15]
	s_add_u32 m0, s18, 0x9000
	s_nop 0
	global_load_lds_dwordx4 v151, s[14:15]
	s_add_u32 m0, s18, 0xa000
	s_nop 0
	global_load_lds_dwordx4 v152, s[16:17]
	s_add_u32 m0, s18, 0xb000
	s_nop 0
	global_load_lds_dwordx4 v153, s[16:17]
.La2_nodma0:
.La2_qk0:
	v_lshrrev_b64 v[188:189], s22, v[154:155]
	v_and_b32_e32 v188, 1, v188
	v_sub_f32_e32 v190, v199, v128
	v_cmp_eq_u32_e32 vcc, 1, v188
	v_xor_b32_e32 v191, 0x80000000, v128
	s_nop 0
	v_cndmask_b32_e32 v114, v190, v191, vcc
	v_mov_b32_e32 v115, v114
	v_mov_b32_e32 v116, v114
	v_mov_b32_e32 v117, v114
	v_lshrrev_b64 v[188:189], s22, v[156:157]
	v_and_b32_e32 v188, 1, v188
	v_sub_f32_e32 v190, v199, v129
	v_cmp_eq_u32_e32 vcc, 1, v188
	v_xor_b32_e32 v191, 0x80000000, v129
	s_nop 0
	v_cndmask_b32_e32 v124, v190, v191, vcc
	v_mov_b32_e32 v125, v124
	v_mov_b32_e32 v126, v124
	v_mov_b32_e32 v127, v124
	ds_read_b128 v[66:69], v132
	ds_read_b128 v[74:77], v132 offset:2048
	ds_read_b128 v[82:85], v132 offset:4096
	ds_read_b128 v[90:93], v132 offset:6144
	ds_read_b128 v[70:73], v133
	ds_read_b128 v[78:81], v133 offset:2048
	ds_read_b128 v[86:89], v133 offset:4096
	ds_read_b128 v[94:97], v133 offset:6144
	s_waitcnt lgkmcnt(7)
	v_mfma_f32_16x16x32_bf16 v[34:37], v[66:69], v[98:101], v[114:117]
	v_mfma_f32_16x16x32_bf16 v[38:41], v[66:69], v[106:109], v[124:127]
	s_waitcnt lgkmcnt(6)
	v_mfma_f32_16x16x32_bf16 v[42:45], v[74:77], v[98:101], v[114:117]
	v_mfma_f32_16x16x32_bf16 v[46:49], v[74:77], v[106:109], v[124:127]
	s_waitcnt lgkmcnt(5)
	v_mfma_f32_16x16x32_bf16 v[50:53], v[82:85], v[98:101], v[114:117]
	v_mfma_f32_16x16x32_bf16 v[54:57], v[82:85], v[106:109], v[124:127]
	s_waitcnt lgkmcnt(4)
	v_mfma_f32_16x16x32_bf16 v[58:61], v[90:93], v[98:101], v[114:117]
	v_mfma_f32_16x16x32_bf16 v[62:65], v[90:93], v[106:109], v[124:127]
	s_waitcnt lgkmcnt(3)
	v_mfma_f32_16x16x32_bf16 v[34:37], v[70:73], v[102:105], v[34:37]
	v_mfma_f32_16x16x32_bf16 v[38:41], v[70:73], v[110:113], v[38:41]
	s_waitcnt lgkmcnt(2)
	v_mfma_f32_16x16x32_bf16 v[42:45], v[78:81], v[102:105], v[42:45]
	v_mfma_f32_16x16x32_bf16 v[46:49], v[78:81], v[110:113], v[46:49]
	s_waitcnt lgkmcnt(1)
	v_mfma_f32_16x16x32_bf16 v[50:53], v[86:89], v[102:105], v[50:53]
	v_mfma_f32_16x16x32_bf16 v[54:57], v[86:89], v[110:113], v[54:57]
	s_waitcnt lgkmcnt(0)
	v_mfma_f32_16x16x32_bf16 v[58:61], v[94:97], v[102:105], v[58:61]
	v_mfma_f32_16x16x32_bf16 v[62:65], v[94:97], v[110:113], v[62:65]
	ds_read_b64 v[66:67], v134 offset:0
	ds_read_b64 v[68:69], v135 offset:0
	ds_read_b64 v[70:71], v134 offset:2048
	ds_read_b64 v[72:73], v135 offset:2048
	ds_read_b64 v[74:75], v134 offset:4096
	ds_read_b64 v[76:77], v135 offset:4096
	ds_read_b64 v[78:79], v134 offset:6144
	ds_read_b64 v[80:81], v135 offset:6144
	ds_read_b64 v[82:83], v148 offset:0
	ds_read_b64 v[84:85], v149 offset:0
	ds_read_b64 v[86:87], v148 offset:2048
	ds_read_b64 v[88:89], v149 offset:2048
	ds_read_b64 v[90:91], v148 offset:4096
	ds_read_b64 v[92:93], v149 offset:4096
	ds_read_b64 v[94:95], v148 offset:6144
	ds_read_b64 v[96:97], v149 offset:6144
	s_cmp_eq_u32 s22, s4
	s_cbranch_scc0 .La2_nodiag0
	v_cmp_le_i32_e64 s[44:45], 0, v158
	s_nop 1
	v_cndmask_b32_e64 v34, v199, v34, s[44:45]
	v_cmp_le_i32_e64 s[46:47], 1, v158
	s_nop 1
	v_cndmask_b32_e64 v35, v199, v35, s[46:47]
	v_cmp_le_i32_e64 s[48:49], 2, v158
	s_nop 1
	v_cndmask_b32_e64 v36, v199, v36, s[48:49]
	v_cmp_le_i32_e64 s[50:51], 3, v158
	s_nop 1
	v_cndmask_b32_e64 v37, v199, v37, s[50:51]
	v_cmp_le_i32_e64 s[44:45], 16, v158
	s_nop 1
	v_cndmask_b32_e64 v42, v199, v42, s[44:45]
	v_cmp_le_i32_e64 s[46:47], 17, v158
	s_nop 1
	v_cndmask_b32_e64 v43, v199, v43, s[46:47]
	v_cmp_le_i32_e64 s[48:49], 18, v158
	s_nop 1
	v_cndmask_b32_e64 v44, v199, v44, s[48:49]
	v_cmp_le_i32_e64 s[50:51], 19, v158
	s_nop 1
	v_cndmask_b32_e64 v45, v199, v45, s[50:51]
	v_cmp_le_i32_e64 s[44:45], 32, v158
	s_nop 1
	v_cndmask_b32_e64 v50, v199, v50, s[44:45]
	v_cmp_le_i32_e64 s[46:47], 33, v158
	s_nop 1
	v_cndmask_b32_e64 v51, v199, v51, s[46:47]
	v_cmp_le_i32_e64 s[48:49], 34, v158
	s_nop 1
	v_cndmask_b32_e64 v52, v199, v52, s[48:49]
	v_cmp_le_i32_e64 s[50:51], 35, v158
	s_nop 1
	v_cndmask_b32_e64 v53, v199, v53, s[50:51]
	v_cmp_le_i32_e64 s[44:45], 48, v158
	s_nop 1
	v_cndmask_b32_e64 v58, v199, v58, s[44:45]
	v_cmp_le_i32_e64 s[46:47], 49, v158
	s_nop 1
	v_cndmask_b32_e64 v59, v199, v59, s[46:47]
	v_cmp_le_i32_e64 s[48:49], 50, v158
	s_nop 1
	v_cndmask_b32_e64 v60, v199, v60, s[48:49]
	v_cmp_le_i32_e64 s[50:51], 51, v158
	s_nop 1
	v_cndmask_b32_e64 v61, v199, v61, s[50:51]
	v_cmp_le_i32_e64 s[44:45], 0, v159
	s_nop 1
	v_cndmask_b32_e64 v38, v199, v38, s[44:45]
	v_cmp_le_i32_e64 s[46:47], 1, v159
	s_nop 1
	v_cndmask_b32_e64 v39, v199, v39, s[46:47]
	v_cmp_le_i32_e64 s[48:49], 2, v159
	s_nop 1
	v_cndmask_b32_e64 v40, v199, v40, s[48:49]
	v_cmp_le_i32_e64 s[50:51], 3, v159
	s_nop 1
	v_cndmask_b32_e64 v41, v199, v41, s[50:51]
	v_cmp_le_i32_e64 s[44:45], 16, v159
	s_nop 1
	v_cndmask_b32_e64 v46, v199, v46, s[44:45]
	v_cmp_le_i32_e64 s[46:47], 17, v159
	s_nop 1
	v_cndmask_b32_e64 v47, v199, v47, s[46:47]
	v_cmp_le_i32_e64 s[48:49], 18, v159
	s_nop 1
	v_cndmask_b32_e64 v48, v199, v48, s[48:49]
	v_cmp_le_i32_e64 s[50:51], 19, v159
	s_nop 1
	v_cndmask_b32_e64 v49, v199, v49, s[50:51]
	v_cmp_le_i32_e64 s[44:45], 32, v159
	s_nop 1
	v_cndmask_b32_e64 v54, v199, v54, s[44:45]
	v_cmp_le_i32_e64 s[46:47], 33, v159
	s_nop 1
	v_cndmask_b32_e64 v55, v199, v55, s[46:47]
	v_cmp_le_i32_e64 s[48:49], 34, v159
	s_nop 1
	v_cndmask_b32_e64 v56, v199, v56, s[48:49]
	v_cmp_le_i32_e64 s[50:51], 35, v159
	s_nop 1
	v_cndmask_b32_e64 v57, v199, v57, s[50:51]
	v_cmp_le_i32_e64 s[44:45], 48, v159
	s_nop 1
	v_cndmask_b32_e64 v62, v199, v62, s[44:45]
	v_cmp_le_i32_e64 s[46:47], 49, v159
	s_nop 1
	v_cndmask_b32_e64 v63, v199, v63, s[46:47]
	v_cmp_le_i32_e64 s[48:49], 50, v159
	s_nop 1
	v_cndmask_b32_e64 v64, v199, v64, s[48:49]
	v_cmp_le_i32_e64 s[50:51], 51, v159
	s_nop 1
	v_cndmask_b32_e64 v65, v199, v65, s[50:51]
.La2_nodiag0:
	s_cmp_eq_u32 s22, s27
	s_cbranch_scc0 .La2_nolow0
	v_cmp_gt_i32_e64 s[44:45], 0, v158
	s_nop 1
	v_cndmask_b32_e64 v34, v199, v34, s[44:45]
	v_cmp_gt_i32_e64 s[46:47], 1, v158
	s_nop 1
	v_cndmask_b32_e64 v35, v199, v35, s[46:47]
	v_cmp_gt_i32_e64 s[48:49], 2, v158
	s_nop 1
	v_cndmask_b32_e64 v36, v199, v36, s[48:49]
	v_cmp_gt_i32_e64 s[50:51], 3, v158
	s_nop 1
	v_cndmask_b32_e64 v37, v199, v37, s[50:51]
	v_cmp_gt_i32_e64 s[44:45], 16, v158
	s_nop 1
	v_cndmask_b32_e64 v42, v199, v42, s[44:45]
	v_cmp_gt_i32_e64 s[46:47], 17, v158
	s_nop 1
	v_cndmask_b32_e64 v43, v199, v43, s[46:47]
	v_cmp_gt_i32_e64 s[48:49], 18, v158
	s_nop 1
	v_cndmask_b32_e64 v44, v199, v44, s[48:49]
	v_cmp_gt_i32_e64 s[50:51], 19, v158
	s_nop 1
	v_cndmask_b32_e64 v45, v199, v45, s[50:51]
	v_cmp_gt_i32_e64 s[44:45], 32, v158
	s_nop 1
	v_cndmask_b32_e64 v50, v199, v50, s[44:45]
	v_cmp_gt_i32_e64 s[46:47], 33, v158
	s_nop 1
	v_cndmask_b32_e64 v51, v199, v51, s[46:47]
	v_cmp_gt_i32_e64 s[48:49], 34, v158
	s_nop 1
	v_cndmask_b32_e64 v52, v199, v52, s[48:49]
	v_cmp_gt_i32_e64 s[50:51], 35, v158
	s_nop 1
	v_cndmask_b32_e64 v53, v199, v53, s[50:51]
	v_cmp_gt_i32_e64 s[44:45], 48, v158
	s_nop 1
	v_cndmask_b32_e64 v58, v199, v58, s[44:45]
	v_cmp_gt_i32_e64 s[46:47], 49, v158
	s_nop 1
	v_cndmask_b32_e64 v59, v199, v59, s[46:47]
	v_cmp_gt_i32_e64 s[48:49], 50, v158
	s_nop 1
	v_cndmask_b32_e64 v60, v199, v60, s[48:49]
	v_cmp_gt_i32_e64 s[50:51], 51, v158
	s_nop 1
	v_cndmask_b32_e64 v61, v199, v61, s[50:51]
	v_cmp_gt_i32_e64 s[44:45], 0, v159
	s_nop 1
	v_cndmask_b32_e64 v38, v199, v38, s[44:45]
	v_cmp_gt_i32_e64 s[46:47], 1, v159
	s_nop 1
	v_cndmask_b32_e64 v39, v199, v39, s[46:47]
	v_cmp_gt_i32_e64 s[48:49], 2, v159
	s_nop 1
	v_cndmask_b32_e64 v40, v199, v40, s[48:49]
	v_cmp_gt_i32_e64 s[50:51], 3, v159
	s_nop 1
	v_cndmask_b32_e64 v41, v199, v41, s[50:51]
	v_cmp_gt_i32_e64 s[44:45], 16, v159
	s_nop 1
	v_cndmask_b32_e64 v46, v199, v46, s[44:45]
	v_cmp_gt_i32_e64 s[46:47], 17, v159
	s_nop 1
	v_cndmask_b32_e64 v47, v199, v47, s[46:47]
	v_cmp_gt_i32_e64 s[48:49], 18, v159
	s_nop 1
	v_cndmask_b32_e64 v48, v199, v48, s[48:49]
	v_cmp_gt_i32_e64 s[50:51], 19, v159
	s_nop 1
	v_cndmask_b32_e64 v49, v199, v49, s[50:51]
	v_cmp_gt_i32_e64 s[44:45], 32, v159
	s_nop 1
	v_cndmask_b32_e64 v54, v199, v54, s[44:45]
	v_cmp_gt_i32_e64 s[46:47], 33, v159
	s_nop 1
	v_cndmask_b32_e64 v55, v199, v55, s[46:47]
	v_cmp_gt_i32_e64 s[48:49], 34, v159
	s_nop 1
	v_cndmask_b32_e64 v56, v199, v56, s[48:49]
	v_cmp_gt_i32_e64 s[50:51], 35, v159
	s_nop 1
	v_cndmask_b32_e64 v57, v199, v57, s[50:51]
	v_cmp_gt_i32_e64 s[44:45], 48, v159
	s_nop 1
	v_cndmask_b32_e64 v62, v199, v62, s[44:45]
	v_cmp_gt_i32_e64 s[46:47], 49, v159
	s_nop 1
	v_cndmask_b32_e64 v63, v199, v63, s[46:47]
	v_cmp_gt_i32_e64 s[48:49], 50, v159
	s_nop 1
	v_cndmask_b32_e64 v64, v199, v64, s[48:49]
	v_cmp_gt_i32_e64 s[50:51], 51, v159
	s_nop 1
	v_cndmask_b32_e64 v65, v199, v65, s[50:51]
.La2_nolow0:
	s_cmp_eq_u32 s24, 0
	s_cbranch_scc0 .La2_slow0
.La2_exp0:
	v_exp_f32_e32 v34, v34
	v_exp_f32_e32 v35, v35
	v_exp_f32_e32 v36, v36
	v_exp_f32_e32 v37, v37
	v_exp_f32_e32 v42, v42
	v_exp_f32_e32 v43, v43
	v_exp_f32_e32 v44, v44
	v_exp_f32_e32 v45, v45
	v_exp_f32_e32 v50, v50
	v_exp_f32_e32 v51, v51
	v_exp_f32_e32 v52, v52
	v_exp_f32_e32 v53, v53
	v_exp_f32_e32 v58, v58
	v_exp_f32_e32 v59, v59
	v_exp_f32_e32 v60, v60
	v_exp_f32_e32 v61, v61
	v_add_f32_e32 v218, v34, v35
	v_add_f32_e32 v218, v218, v36
	v_add_f32_e32 v218, v218, v37
	v_add_f32_e32 v218, v218, v42
	v_add_f32_e32 v218, v218, v43
	v_add_f32_e32 v218, v218, v44
	v_add_f32_e32 v218, v218, v45
	v_add_f32_e32 v218, v218, v50
	v_add_f32_e32 v218, v218, v51
	v_add_f32_e32 v218, v218, v52
	v_add_f32_e32 v218, v218, v53
	v_add_f32_e32 v218, v218, v58
	v_add_f32_e32 v218, v218, v59
	v_add_f32_e32 v218, v218, v60
	v_add_f32_e32 v218, v218, v61
	v_exp_f32_e32 v38, v38
	v_exp_f32_e32 v39, v39
	v_exp_f32_e32 v40, v40
	v_exp_f32_e32 v41, v41
	v_exp_f32_e32 v46, v46
	v_exp_f32_e32 v47, v47
	v_exp_f32_e32 v48, v48
	v_exp_f32_e32 v49, v49
	v_exp_f32_e32 v54, v54
	v_exp_f32_e32 v55, v55
	v_exp_f32_e32 v56, v56
	v_exp_f32_e32 v57, v57
	v_exp_f32_e32 v62, v62
	v_exp_f32_e32 v63, v63
	v_exp_f32_e32 v64, v64
	v_exp_f32_e32 v65, v65
	v_add_f32_e32 v219, v38, v39
	v_add_f32_e32 v219, v219, v40
	v_add_f32_e32 v219, v219, v41
	v_add_f32_e32 v219, v219, v46
	v_add_f32_e32 v219, v219, v47
	v_add_f32_e32 v219, v219, v48
	v_add_f32_e32 v219, v219, v49
	v_add_f32_e32 v219, v219, v54
	v_add_f32_e32 v219, v219, v55
	v_add_f32_e32 v219, v219, v56
	v_add_f32_e32 v219, v219, v57
	v_add_f32_e32 v219, v219, v62
	v_add_f32_e32 v219, v219, v63
	v_add_f32_e32 v219, v219, v64
	v_add_f32_e32 v219, v219, v65
	v_cmp_lt_f32_e32 vcc, 0x4e800000, v218
	s_mov_b32 s28, 0x4e800000
	v_cmp_lt_f32_e64 s[44:45], s28, v219
	s_or_b64 vcc, vcc, s[44:45]
	s_cbranch_vccnz .La2_over0
	v_add_f32_e32 v130, v130, v218
	v_add_f32_e32 v131, v131, v219
	v_cvt_pk_bf16_f32 v34, v34, v35
	v_cvt_pk_bf16_f32 v35, v36, v37
	v_cvt_pk_bf16_f32 v36, v42, v43
	v_cvt_pk_bf16_f32 v37, v44, v45
	v_cvt_pk_bf16_f32 v50, v50, v51
	v_cvt_pk_bf16_f32 v51, v52, v53
	v_cvt_pk_bf16_f32 v52, v58, v59
	v_cvt_pk_bf16_f32 v53, v60, v61
	v_cvt_pk_bf16_f32 v38, v38, v39
	v_cvt_pk_bf16_f32 v39, v40, v41
	v_cvt_pk_bf16_f32 v40, v46, v47
	v_cvt_pk_bf16_f32 v41, v48, v49
	v_cvt_pk_bf16_f32 v54, v54, v55
	v_cvt_pk_bf16_f32 v55, v56, v57
	v_cvt_pk_bf16_f32 v56, v62, v63
	v_cvt_pk_bf16_f32 v57, v64, v65
	s_waitcnt lgkmcnt(0)
	v_mfma_f32_16x16x32_bf16 v[2:5], v[66:69], v[34:37], v[2:5]
	v_mfma_f32_16x16x32_bf16 v[6:9], v[66:69], v[38:41], v[6:9]
	v_mfma_f32_16x16x32_bf16 v[10:13], v[70:73], v[34:37], v[10:13]
	v_mfma_f32_16x16x32_bf16 v[14:17], v[70:73], v[38:41], v[14:17]
	v_mfma_f32_16x16x32_bf16 v[18:21], v[74:77], v[34:37], v[18:21]
	v_mfma_f32_16x16x32_bf16 v[22:25], v[74:77], v[38:41], v[22:25]
	v_mfma_f32_16x16x32_bf16 v[26:29], v[78:81], v[34:37], v[26:29]
	v_mfma_f32_16x16x32_bf16 v[30:33], v[78:81], v[38:41], v[30:33]
	v_mfma_f32_16x16x32_bf16 v[2:5], v[82:85], v[50:53], v[2:5]
	v_mfma_f32_16x16x32_bf16 v[6:9], v[82:85], v[54:57], v[6:9]
	v_mfma_f32_16x16x32_bf16 v[10:13], v[86:89], v[50:53], v[10:13]
	v_mfma_f32_16x16x32_bf16 v[14:17], v[86:89], v[54:57], v[14:17]
	v_mfma_f32_16x16x32_bf16 v[18:21], v[90:93], v[50:53], v[18:21]
	v_mfma_f32_16x16x32_bf16 v[22:25], v[90:93], v[54:57], v[22:25]
	v_mfma_f32_16x16x32_bf16 v[26:29], v[94:97], v[50:53], v[26:29]
	v_mfma_f32_16x16x32_bf16 v[30:33], v[94:97], v[54:57], v[30:33]
	s_waitcnt vmcnt(0)
	s_barrier
	s_mov_b32 s22, s23
	s_cmp_eq_u32 s25, 1
	s_cbranch_scc1 .La2_done
	s_branch .La2_it1
.La2_over0:
	s_mov_b32 s24, 1
	s_branch .La2_qk0
.La2_slow0:
	v_max3_f32 v188, v34, v35, v36
	v_max3_f32 v188, v188, v37, v42
	v_max3_f32 v188, v188, v43, v44
	v_max3_f32 v188, v188, v45, v50
	v_max3_f32 v188, v188, v51, v52
	v_max3_f32 v188, v188, v53, v58
	v_max3_f32 v188, v188, v59, v60
	v_max_f32_e32 v188, v188, v61
	s_nop 0
	ds_swizzle_b32 v189, v188 offset:0x401f
	s_waitcnt lgkmcnt(0)
	v_max_f32_e32 v188, v188, v189
	s_nop 0
	ds_bpermute_b32 v189, v214, v188
	s_waitcnt lgkmcnt(0)
	v_max_f32_e32 v188, v188, v189
	v_cmp_lt_f32_e32 vcc, 0xf0a18f08, v188
	s_nop 1
	v_cndmask_b32_e32 v190, 0, v188, vcc
	v_add_f32_e32 v128, v128, v190
	v_sub_f32_e32 v191, 0, v190
	v_min_f32_e32 v191, 0x42fc0000, v191
	v_exp_f32_e32 v191, v191
	v_sub_f32_e32 v34, v34, v190
	v_sub_f32_e32 v35, v35, v190
	v_sub_f32_e32 v36, v36, v190
	v_sub_f32_e32 v37, v37, v190
	v_sub_f32_e32 v42, v42, v190
	v_sub_f32_e32 v43, v43, v190
	v_sub_f32_e32 v44, v44, v190
	v_sub_f32_e32 v45, v45, v190
	v_sub_f32_e32 v50, v50, v190
	v_sub_f32_e32 v51, v51, v190
	v_sub_f32_e32 v52, v52, v190
	v_sub_f32_e32 v53, v53, v190
	v_sub_f32_e32 v58, v58, v190
	v_sub_f32_e32 v59, v59, v190
	v_sub_f32_e32 v60, v60, v190
	v_sub_f32_e32 v61, v61, v190
	v_mul_f32_e32 v130, v130, v191
	v_mul_f32_e32 v2, v2, v191
	v_mul_f32_e32 v3, v3, v191
	v_mul_f32_e32 v4, v4, v191
	v_mul_f32_e32 v5, v5, v191
	v_mul_f32_e32 v10, v10, v191
	v_mul_f32_e32 v11, v11, v191
	v_mul_f32_e32 v12, v12, v191
	v_mul_f32_e32 v13, v13, v191
	v_mul_f32_e32 v18, v18, v191
	v_mul_f32_e32 v19, v19, v191
	v_mul_f32_e32 v20, v20, v191
	v_mul_f32_e32 v21, v21, v191
	v_mul_f32_e32 v26, v26, v191
	v_mul_f32_e32 v27, v27, v191
	v_mul_f32_e32 v28, v28, v191
	v_mul_f32_e32 v29, v29, v191
	v_max3_f32 v188, v38, v39, v40
	v_max3_f32 v188, v188, v41, v46
	v_max3_f32 v188, v188, v47, v48
	v_max3_f32 v188, v188, v49, v54
	v_max3_f32 v188, v188, v55, v56
	v_max3_f32 v188, v188, v57, v62
	v_max3_f32 v188, v188, v63, v64
	v_max_f32_e32 v188, v188, v65
	s_nop 0
	ds_swizzle_b32 v189, v188 offset:0x401f
	s_waitcnt lgkmcnt(0)
	v_max_f32_e32 v188, v188, v189
	s_nop 0
	ds_bpermute_b32 v189, v214, v188
	s_waitcnt lgkmcnt(0)
	v_max_f32_e32 v188, v188, v189
	v_cmp_lt_f32_e32 vcc, 0xf0a18f08, v188
	s_nop 1
	v_cndmask_b32_e32 v190, 0, v188, vcc
	v_add_f32_e32 v129, v129, v190
	v_sub_f32_e32 v191, 0, v190
	v_min_f32_e32 v191, 0x42fc0000, v191
	v_exp_f32_e32 v191, v191
	v_sub_f32_e32 v38, v38, v190
	v_sub_f32_e32 v39, v39, v190
	v_sub_f32_e32 v40, v40, v190
	v_sub_f32_e32 v41, v41, v190
	v_sub_f32_e32 v46, v46, v190
	v_sub_f32_e32 v47, v47, v190
	v_sub_f32_e32 v48, v48, v190
	v_sub_f32_e32 v49, v49, v190
	v_sub_f32_e32 v54, v54, v190
	v_sub_f32_e32 v55, v55, v190
	v_sub_f32_e32 v56, v56, v190
	v_sub_f32_e32 v57, v57, v190
	v_sub_f32_e32 v62, v62, v190
	v_sub_f32_e32 v63, v63, v190
	v_sub_f32_e32 v64, v64, v190
	v_sub_f32_e32 v65, v65, v190
	v_mul_f32_e32 v131, v131, v191
	v_mul_f32_e32 v6, v6, v191
	v_mul_f32_e32 v7, v7, v191
	v_mul_f32_e32 v8, v8, v191
	v_mul_f32_e32 v9, v9, v191
	v_mul_f32_e32 v14, v14, v191
	v_mul_f32_e32 v15, v15, v191
	v_mul_f32_e32 v16, v16, v191
	v_mul_f32_e32 v17, v17, v191
	v_mul_f32_e32 v22, v22, v191
	v_mul_f32_e32 v23, v23, v191
	v_mul_f32_e32 v24, v24, v191
	v_mul_f32_e32 v25, v25, v191
	v_mul_f32_e32 v30, v30, v191
	v_mul_f32_e32 v31, v31, v191
	v_mul_f32_e32 v32, v32, v191
	v_mul_f32_e32 v33, v33, v191
	s_mov_b32 s24, 0
	s_branch .La2_exp0
.La2_it1:
	s_cmp_eq_u64 s[20:21], 0
	s_cselect_b32 s25, 1, 0
	s_ff1_i32_b64 s23, s[20:21]
	s_add_u32 s28, s20, -1
	s_addc_u32 s29, s21, -1
	s_and_b64 s[20:21], s[20:21], s[28:29]
	s_cmp_eq_u32 s25, 1
	s_cbranch_scc1 .La2_nodma1
	s_lshl_b32 s28, s23, 13
	s_add_u32 s14, s10, s28
	s_addc_u32 s15, s11, 0
	s_lshl_b32 s28, s23, 7
	s_add_u32 s16, s12, s28
	s_addc_u32 s17, s13, 0
	s_mov_b32 m0, s18
	s_nop 0
	global_load_lds_dwordx4 v150, s[14:15]
	s_add_u32 m0, s18, 0x1000
	s_nop 0
	global_load_lds_dwordx4 v151, s[14:15]
	s_add_u32 m0, s18, 0x2000
	s_nop 0
	global_load_lds_dwordx4 v152, s[16:17]
	s_add_u32 m0, s18, 0x3000
	s_nop 0
	global_load_lds_dwordx4 v153, s[16:17]
.La2_nodma1:
.La2_qk1:
	v_lshrrev_b64 v[188:189], s22, v[154:155]
	v_and_b32_e32 v188, 1, v188
	v_sub_f32_e32 v190, v199, v128
	v_cmp_eq_u32_e32 vcc, 1, v188
	v_xor_b32_e32 v191, 0x80000000, v128
	s_nop 0
	v_cndmask_b32_e32 v114, v190, v191, vcc
	v_mov_b32_e32 v115, v114
	v_mov_b32_e32 v116, v114
	v_mov_b32_e32 v117, v114
	v_lshrrev_b64 v[188:189], s22, v[156:157]
	v_and_b32_e32 v188, 1, v188
	v_sub_f32_e32 v190, v199, v129
	v_cmp_eq_u32_e32 vcc, 1, v188
	v_xor_b32_e32 v191, 0x80000000, v129
	s_nop 0
	v_cndmask_b32_e32 v124, v190, v191, vcc
	v_mov_b32_e32 v125, v124
	v_mov_b32_e32 v126, v124
	v_mov_b32_e32 v127, v124
	ds_read_b128 v[66:69], v132 offset:32768
	ds_read_b128 v[74:77], v132 offset:34816
	ds_read_b128 v[82:85], v132 offset:36864
	ds_read_b128 v[90:93], v132 offset:38912
	ds_read_b128 v[70:73], v133 offset:32768
	ds_read_b128 v[78:81], v133 offset:34816
	ds_read_b128 v[86:89], v133 offset:36864
	ds_read_b128 v[94:97], v133 offset:38912
	s_waitcnt lgkmcnt(7)
	v_mfma_f32_16x16x32_bf16 v[34:37], v[66:69], v[98:101], v[114:117]
	v_mfma_f32_16x16x32_bf16 v[38:41], v[66:69], v[106:109], v[124:127]
	s_waitcnt lgkmcnt(6)
	v_mfma_f32_16x16x32_bf16 v[42:45], v[74:77], v[98:101], v[114:117]
	v_mfma_f32_16x16x32_bf16 v[46:49], v[74:77], v[106:109], v[124:127]
	s_waitcnt lgkmcnt(5)
	v_mfma_f32_16x16x32_bf16 v[50:53], v[82:85], v[98:101], v[114:117]
	v_mfma_f32_16x16x32_bf16 v[54:57], v[82:85], v[106:109], v[124:127]
	s_waitcnt lgkmcnt(4)
	v_mfma_f32_16x16x32_bf16 v[58:61], v[90:93], v[98:101], v[114:117]
	v_mfma_f32_16x16x32_bf16 v[62:65], v[90:93], v[106:109], v[124:127]
	s_waitcnt lgkmcnt(3)
	v_mfma_f32_16x16x32_bf16 v[34:37], v[70:73], v[102:105], v[34:37]
	v_mfma_f32_16x16x32_bf16 v[38:41], v[70:73], v[110:113], v[38:41]
	s_waitcnt lgkmcnt(2)
	v_mfma_f32_16x16x32_bf16 v[42:45], v[78:81], v[102:105], v[42:45]
	v_mfma_f32_16x16x32_bf16 v[46:49], v[78:81], v[110:113], v[46:49]
	s_waitcnt lgkmcnt(1)
	v_mfma_f32_16x16x32_bf16 v[50:53], v[86:89], v[102:105], v[50:53]
	v_mfma_f32_16x16x32_bf16 v[54:57], v[86:89], v[110:113], v[54:57]
	s_waitcnt lgkmcnt(0)
	v_mfma_f32_16x16x32_bf16 v[58:61], v[94:97], v[102:105], v[58:61]
	v_mfma_f32_16x16x32_bf16 v[62:65], v[94:97], v[110:113], v[62:65]
	ds_read_b64 v[66:67], v134 offset:32768
	ds_read_b64 v[68:69], v135 offset:32768
	ds_read_b64 v[70:71], v134 offset:34816
	ds_read_b64 v[72:73], v135 offset:34816
	ds_read_b64 v[74:75], v134 offset:36864
	ds_read_b64 v[76:77], v135 offset:36864
	ds_read_b64 v[78:79], v134 offset:38912
	ds_read_b64 v[80:81], v135 offset:38912
	ds_read_b64 v[82:83], v148 offset:32768
	ds_read_b64 v[84:85], v149 offset:32768
	ds_read_b64 v[86:87], v148 offset:34816
	ds_read_b64 v[88:89], v149 offset:34816
	ds_read_b64 v[90:91], v148 offset:36864
	ds_read_b64 v[92:93], v149 offset:36864
	ds_read_b64 v[94:95], v148 offset:38912
	ds_read_b64 v[96:97], v149 offset:38912
	s_cmp_eq_u32 s22, s4
	s_cbranch_scc0 .La2_nodiag1
	v_cmp_le_i32_e64 s[44:45], 0, v158
	s_nop 1
	v_cndmask_b32_e64 v34, v199, v34, s[44:45]
	v_cmp_le_i32_e64 s[46:47], 1, v158
	s_nop 1
	v_cndmask_b32_e64 v35, v199, v35, s[46:47]
	v_cmp_le_i32_e64 s[48:49], 2, v158
	s_nop 1
	v_cndmask_b32_e64 v36, v199, v36, s[48:49]
	v_cmp_le_i32_e64 s[50:51], 3, v158
	s_nop 1
	v_cndmask_b32_e64 v37, v199, v37, s[50:51]
	v_cmp_le_i32_e64 s[44:45], 16, v158
	s_nop 1
	v_cndmask_b32_e64 v42, v199, v42, s[44:45]
	v_cmp_le_i32_e64 s[46:47], 17, v158
	s_nop 1
	v_cndmask_b32_e64 v43, v199, v43, s[46:47]
	v_cmp_le_i32_e64 s[48:49], 18, v158
	s_nop 1
	v_cndmask_b32_e64 v44, v199, v44, s[48:49]
	v_cmp_le_i32_e64 s[50:51], 19, v158
	s_nop 1
	v_cndmask_b32_e64 v45, v199, v45, s[50:51]
	v_cmp_le_i32_e64 s[44:45], 32, v158
	s_nop 1
	v_cndmask_b32_e64 v50, v199, v50, s[44:45]
	v_cmp_le_i32_e64 s[46:47], 33, v158
	s_nop 1
	v_cndmask_b32_e64 v51, v199, v51, s[46:47]
	v_cmp_le_i32_e64 s[48:49], 34, v158
	s_nop 1
	v_cndmask_b32_e64 v52, v199, v52, s[48:49]
	v_cmp_le_i32_e64 s[50:51], 35, v158
	s_nop 1
	v_cndmask_b32_e64 v53, v199, v53, s[50:51]
	v_cmp_le_i32_e64 s[44:45], 48, v158
	s_nop 1
	v_cndmask_b32_e64 v58, v199, v58, s[44:45]
	v_cmp_le_i32_e64 s[46:47], 49, v158
	s_nop 1
	v_cndmask_b32_e64 v59, v199, v59, s[46:47]
	v_cmp_le_i32_e64 s[48:49], 50, v158
	s_nop 1
	v_cndmask_b32_e64 v60, v199, v60, s[48:49]
	v_cmp_le_i32_e64 s[50:51], 51, v158
	s_nop 1
	v_cndmask_b32_e64 v61, v199, v61, s[50:51]
	v_cmp_le_i32_e64 s[44:45], 0, v159
	s_nop 1
	v_cndmask_b32_e64 v38, v199, v38, s[44:45]
	v_cmp_le_i32_e64 s[46:47], 1, v159
	s_nop 1
	v_cndmask_b32_e64 v39, v199, v39, s[46:47]
	v_cmp_le_i32_e64 s[48:49], 2, v159
	s_nop 1
	v_cndmask_b32_e64 v40, v199, v40, s[48:49]
	v_cmp_le_i32_e64 s[50:51], 3, v159
	s_nop 1
	v_cndmask_b32_e64 v41, v199, v41, s[50:51]
	v_cmp_le_i32_e64 s[44:45], 16, v159
	s_nop 1
	v_cndmask_b32_e64 v46, v199, v46, s[44:45]
	v_cmp_le_i32_e64 s[46:47], 17, v159
	s_nop 1
	v_cndmask_b32_e64 v47, v199, v47, s[46:47]
	v_cmp_le_i32_e64 s[48:49], 18, v159
	s_nop 1
	v_cndmask_b32_e64 v48, v199, v48, s[48:49]
	v_cmp_le_i32_e64 s[50:51], 19, v159
	s_nop 1
	v_cndmask_b32_e64 v49, v199, v49, s[50:51]
	v_cmp_le_i32_e64 s[44:45], 32, v159
	s_nop 1
	v_cndmask_b32_e64 v54, v199, v54, s[44:45]
	v_cmp_le_i32_e64 s[46:47], 33, v159
	s_nop 1
	v_cndmask_b32_e64 v55, v199, v55, s[46:47]
	v_cmp_le_i32_e64 s[48:49], 34, v159
	s_nop 1
	v_cndmask_b32_e64 v56, v199, v56, s[48:49]
	v_cmp_le_i32_e64 s[50:51], 35, v159
	s_nop 1
	v_cndmask_b32_e64 v57, v199, v57, s[50:51]
	v_cmp_le_i32_e64 s[44:45], 48, v159
	s_nop 1
	v_cndmask_b32_e64 v62, v199, v62, s[44:45]
	v_cmp_le_i32_e64 s[46:47], 49, v159
	s_nop 1
	v_cndmask_b32_e64 v63, v199, v63, s[46:47]
	v_cmp_le_i32_e64 s[48:49], 50, v159
	s_nop 1
	v_cndmask_b32_e64 v64, v199, v64, s[48:49]
	v_cmp_le_i32_e64 s[50:51], 51, v159
	s_nop 1
	v_cndmask_b32_e64 v65, v199, v65, s[50:51]

.La2_done:
	s_nop 7
	s_nop 1
	s_cmp_eq_u32 s26, 0
	s_cbranch_scc0 .La2_fin_win
	ds_swizzle_b32 v189, v130 offset:0x401f
	v_lshlrev_b32_e32 v190, 16, v160
	v_mul_f32_e32 v190, 0xbfb8aa3b, v190
	v_exp_f32_e32 v190, v190
	s_waitcnt lgkmcnt(0)
	v_add_f32_e32 v188, v130, v189
	v_add_f32_e32 v190, 1.0, v190
	ds_bpermute_b32 v189, v214, v188
	v_rcp_f32_e32 v190, v190
	s_waitcnt lgkmcnt(0)
	v_add_f32_e32 v188, v188, v189
	v_max_f32_e32 v188, 0xda24260, v188
	v_div_scale_f32 v206, s[44:45], v188, v188, v190
	v_rcp_f32_e32 v207, v206
	s_nop 0
	v_fma_f32 v208, -v206, v207, 1.0
	v_fmac_f32_e32 v207, v208, v207
	v_div_scale_f32 v208, vcc, v190, v188, v190
	v_mul_f32_e32 v209, v208, v207
	v_fma_f32 v189, -v206, v209, v208
	v_fmac_f32_e32 v209, v189, v207
	v_fma_f32 v206, -v206, v209, v208
	v_div_fmas_f32 v206, v206, v207, v209
	v_div_fixup_f32 v191, v206, v188, v190
	v_lshlrev_b32_e32 v210, 16, v147
	v_and_b32_e32 v211, 0xffff0000, v147
	v_fmac_f32_e32 v210, v2, v191
	v_fmac_f32_e32 v211, v3, v191
	v_cvt_pk_bf16_f32 v147, v210, v211
	v_lshlrev_b32_e32 v210, 16, v146
	v_and_b32_e32 v211, 0xffff0000, v146
	v_fmac_f32_e32 v210, v4, v191
	v_fmac_f32_e32 v211, v5, v191
	v_cvt_pk_bf16_f32 v146, v210, v211
	v_lshlrev_b32_e32 v210, 16, v145
	v_and_b32_e32 v211, 0xffff0000, v145
	v_fmac_f32_e32 v210, v10, v191
	v_fmac_f32_e32 v211, v11, v191
	v_cvt_pk_bf16_f32 v145, v210, v211
	v_lshlrev_b32_e32 v210, 16, v144
	v_and_b32_e32 v211, 0xffff0000, v144
	v_fmac_f32_e32 v210, v12, v191
	v_fmac_f32_e32 v211, v13, v191
	v_cvt_pk_bf16_f32 v144, v210, v211
	v_lshlrev_b32_e32 v210, 16, v143
	v_and_b32_e32 v211, 0xffff0000, v143
	v_fmac_f32_e32 v210, v18, v191
	v_fmac_f32_e32 v211, v19, v191
	v_cvt_pk_bf16_f32 v143, v210, v211
	v_lshlrev_b32_e32 v210, 16, v142
	v_and_b32_e32 v211, 0xffff0000, v142
	v_fmac_f32_e32 v210, v20, v191
	v_fmac_f32_e32 v211, v21, v191
	v_cvt_pk_bf16_f32 v142, v210, v211
	v_lshlrev_b32_e32 v210, 16, v141
	v_and_b32_e32 v211, 0xffff0000, v141
	v_fmac_f32_e32 v210, v26, v191
	v_fmac_f32_e32 v211, v27, v191
	v_cvt_pk_bf16_f32 v141, v210, v211
	v_lshlrev_b32_e32 v210, 16, v140
	v_and_b32_e32 v211, 0xffff0000, v140
	v_fmac_f32_e32 v210, v28, v191
	v_fmac_f32_e32 v211, v29, v191
	v_cvt_pk_bf16_f32 v140, v210, v211
	ds_swizzle_b32 v189, v131 offset:0x401f
	v_lshlrev_b32_e32 v190, 16, v161
	v_mul_f32_e32 v190, 0xbfb8aa3b, v190
	v_exp_f32_e32 v190, v190
	s_waitcnt lgkmcnt(0)
	v_add_f32_e32 v188, v131, v189
	v_add_f32_e32 v190, 1.0, v190
	ds_bpermute_b32 v189, v214, v188
	v_rcp_f32_e32 v190, v190
	s_waitcnt lgkmcnt(0)
	v_add_f32_e32 v188, v188, v189
	v_max_f32_e32 v188, 0xda24260, v188
	v_div_scale_f32 v206, s[44:45], v188, v188, v190
	v_rcp_f32_e32 v207, v206
	s_nop 0
	v_fma_f32 v208, -v206, v207, 1.0
	v_fmac_f32_e32 v207, v208, v207
	v_div_scale_f32 v208, vcc, v190, v188, v190
	v_mul_f32_e32 v209, v208, v207
	v_fma_f32 v189, -v206, v209, v208
	v_fmac_f32_e32 v209, v189, v207
	v_fma_f32 v206, -v206, v209, v208
	v_div_fmas_f32 v206, v206, v207, v209
	v_div_fixup_f32 v191, v206, v188, v190
	v_lshlrev_b32_e32 v210, 16, v139
	v_and_b32_e32 v211, 0xffff0000, v139
	v_fmac_f32_e32 v210, v6, v191
	v_fmac_f32_e32 v211, v7, v191
	v_cvt_pk_bf16_f32 v139, v210, v211
	v_lshlrev_b32_e32 v210, 16, v138
	v_and_b32_e32 v211, 0xffff0000, v138
	v_fmac_f32_e32 v210, v8, v191
	v_fmac_f32_e32 v211, v9, v191
	v_cvt_pk_bf16_f32 v138, v210, v211
	v_lshlrev_b32_e32 v210, 16, v137
	v_and_b32_e32 v211, 0xffff0000, v137
	v_fmac_f32_e32 v210, v14, v191
	v_fmac_f32_e32 v211, v15, v191
	v_cvt_pk_bf16_f32 v137, v210, v211
	v_lshlrev_b32_e32 v210, 16, v136
	v_and_b32_e32 v211, 0xffff0000, v136
	v_fmac_f32_e32 v210, v16, v191
	v_fmac_f32_e32 v211, v17, v191
	v_cvt_pk_bf16_f32 v136, v210, v211
	v_lshlrev_b32_e32 v210, 16, v123
	v_and_b32_e32 v211, 0xffff0000, v123
	v_fmac_f32_e32 v210, v22, v191
	v_fmac_f32_e32 v211, v23, v191
	v_cvt_pk_bf16_f32 v123, v210, v211
	v_lshlrev_b32_e32 v210, 16, v122
	v_and_b32_e32 v211, 0xffff0000, v122
	v_fmac_f32_e32 v210, v24, v191
	v_fmac_f32_e32 v211, v25, v191
	v_cvt_pk_bf16_f32 v122, v210, v211
	v_lshlrev_b32_e32 v210, 16, v121
	v_and_b32_e32 v211, 0xffff0000, v121
	v_fmac_f32_e32 v210, v30, v191
	v_fmac_f32_e32 v211, v31, v191
	v_cvt_pk_bf16_f32 v121, v210, v211
	v_lshlrev_b32_e32 v210, 16, v120
	v_and_b32_e32 v211, 0xffff0000, v120
	v_fmac_f32_e32 v210, v32, v191
	v_fmac_f32_e32 v211, v33, v191
	v_cvt_pk_bf16_f32 v120, v210, v211
	v_readlane_b32 s10, v237, 49
	v_readlane_b32 s11, v237, 50
	s_lshl_b32 s28, s6, 19
	s_add_u32 s10, s10, s28
	s_addc_u32 s11, s11, 0
	v_readlane_b32 s12, v237, 53
	v_readlane_b32 s13, v237, 54
	s_mul_i32 s28, s6, 0x82000
	s_add_u32 s12, s12, s28
	s_addc_u32 s13, s13, 0
	s_add_i32 s27, s4, -8
	s_max_i32 s28, s27, 0
	s_add_i32 s29, s4, 1
	s_sub_i32 s29, s29, s28
	s_bfm_b64 s[20:21], s29, s28
	v_mov_b32_e32 v154, -1
	v_mov_b32_e32 v155, -1
	v_mov_b32_e32 v156, -1
	v_mov_b32_e32 v157, -1
	s_mov_b32 s26, 1
	v_mov_b32_e32 v128, 0
	v_mov_b32_e32 v130, 0
	v_mov_b32_e32 v129, 0
	v_mov_b32_e32 v131, 0
	v_mov_b32_e32 v2, 0
	v_mov_b32_e32 v3, 0
	v_mov_b32_e32 v4, 0
	v_mov_b32_e32 v5, 0
	v_mov_b32_e32 v6, 0
	v_mov_b32_e32 v7, 0
	v_mov_b32_e32 v8, 0
	v_mov_b32_e32 v9, 0
	v_mov_b32_e32 v10, 0
	v_mov_b32_e32 v11, 0
	v_mov_b32_e32 v12, 0
	v_mov_b32_e32 v13, 0
	v_mov_b32_e32 v14, 0
	v_mov_b32_e32 v15, 0
	v_mov_b32_e32 v16, 0
	v_mov_b32_e32 v17, 0
	v_mov_b32_e32 v18, 0
	v_mov_b32_e32 v19, 0
	v_mov_b32_e32 v20, 0
	v_mov_b32_e32 v21, 0
	v_mov_b32_e32 v22, 0
	v_mov_b32_e32 v23, 0
	v_mov_b32_e32 v24, 0
	v_mov_b32_e32 v25, 0
	v_mov_b32_e32 v26, 0
	v_mov_b32_e32 v27, 0
	v_mov_b32_e32 v28, 0
	v_mov_b32_e32 v29, 0
	v_mov_b32_e32 v30, 0
	v_mov_b32_e32 v31, 0
	v_mov_b32_e32 v32, 0
	v_mov_b32_e32 v33, 0
	s_mov_b32 s24, 1
	s_ff1_i32_b64 s22, s[20:21]
	s_add_u32 s28, s20, -1
	s_addc_u32 s29, s21, -1
	s_and_b64 s[20:21], s[20:21], s[28:29]
	s_lshl_b32 s28, s22, 13
	s_add_u32 s14, s10, s28
	s_addc_u32 s15, s11, 0
	s_lshl_b32 s28, s22, 7
	s_add_u32 s16, s12, s28
	s_addc_u32 s17, s13, 0
	s_mov_b32 m0, s18
	s_nop 0
	global_load_lds_dwordx4 v150, s[14:15]
	s_add_u32 m0, s18, 0x1000
	s_nop 0
	global_load_lds_dwordx4 v151, s[14:15]
	s_add_u32 m0, s18, 0x2000
	s_nop 0
	global_load_lds_dwordx4 v152, s[16:17]
	s_add_u32 m0, s18, 0x3000
	s_nop 0
	global_load_lds_dwordx4 v153, s[16:17]
	s_waitcnt vmcnt(0)
	s_barrier
	s_branch .La2_it0
.La2_fin_win:
	ds_swizzle_b32 v189, v130 offset:0x401f
	v_lshlrev_b32_e32 v190, 16, v182
	v_mul_f32_e32 v190, 0xbfb8aa3b, v190
	v_exp_f32_e32 v190, v190
	s_waitcnt lgkmcnt(0)
	v_add_f32_e32 v188, v130, v189
	v_add_f32_e32 v190, 1.0, v190
	ds_bpermute_b32 v189, v214, v188
	v_rcp_f32_e32 v190, v190
	s_waitcnt lgkmcnt(0)
	v_add_f32_e32 v188, v188, v189
	v_max_f32_e32 v188, 0xda24260, v188
	v_div_scale_f32 v206, s[44:45], v188, v188, v190
	v_rcp_f32_e32 v207, v206
	s_nop 0
	v_fma_f32 v208, -v206, v207, 1.0
	v_fmac_f32_e32 v207, v208, v207
	v_div_scale_f32 v208, vcc, v190, v188, v190
	v_mul_f32_e32 v209, v208, v207
	v_fma_f32 v189, -v206, v209, v208
	v_fmac_f32_e32 v209, v189, v207
	v_fma_f32 v206, -v206, v209, v208
	v_div_fmas_f32 v206, v206, v207, v209
	v_div_fixup_f32 v191, v206, v188, v190
	v_lshlrev_b32_e32 v210, 16, v147
	v_and_b32_e32 v211, 0xffff0000, v147
	v_fmac_f32_e32 v210, v2, v191
	v_fmac_f32_e32 v211, v3, v191
	v_cvt_pk_bf16_f32 v147, v210, v211
	v_lshlrev_b32_e32 v210, 16, v146
	v_and_b32_e32 v211, 0xffff0000, v146
	v_fmac_f32_e32 v210, v4, v191
	v_fmac_f32_e32 v211, v5, v191
	v_cvt_pk_bf16_f32 v146, v210, v211
	v_lshlrev_b32_e32 v210, 16, v145
	v_and_b32_e32 v211, 0xffff0000, v145
	v_fmac_f32_e32 v210, v10, v191
	v_fmac_f32_e32 v211, v11, v191
	v_cvt_pk_bf16_f32 v145, v210, v211
	v_lshlrev_b32_e32 v210, 16, v144
	v_and_b32_e32 v211, 0xffff0000, v144
	v_fmac_f32_e32 v210, v12, v191
	v_fmac_f32_e32 v211, v13, v191
	v_cvt_pk_bf16_f32 v144, v210, v211
	v_lshlrev_b32_e32 v210, 16, v143
	v_and_b32_e32 v211, 0xffff0000, v143
	v_fmac_f32_e32 v210, v18, v191
	v_fmac_f32_e32 v211, v19, v191
	v_cvt_pk_bf16_f32 v143, v210, v211
	v_lshlrev_b32_e32 v210, 16, v142
	v_and_b32_e32 v211, 0xffff0000, v142
	v_fmac_f32_e32 v210, v20, v191
	v_fmac_f32_e32 v211, v21, v191
	v_cvt_pk_bf16_f32 v142, v210, v211
	v_lshlrev_b32_e32 v210, 16, v141
	v_and_b32_e32 v211, 0xffff0000, v141
	v_fmac_f32_e32 v210, v26, v191
	v_fmac_f32_e32 v211, v27, v191
	v_cvt_pk_bf16_f32 v141, v210, v211
	v_lshlrev_b32_e32 v210, 16, v140
	v_and_b32_e32 v211, 0xffff0000, v140
	v_fmac_f32_e32 v210, v28, v191
	v_fmac_f32_e32 v211, v29, v191
	v_cvt_pk_bf16_f32 v140, v210, v211
	ds_swizzle_b32 v189, v131 offset:0x401f
	v_lshlrev_b32_e32 v190, 16, v183
	v_mul_f32_e32 v190, 0xbfb8aa3b, v190
	v_exp_f32_e32 v190, v190
	s_waitcnt lgkmcnt(0)
	v_add_f32_e32 v188, v131, v189
	v_add_f32_e32 v190, 1.0, v190
	ds_bpermute_b32 v189, v214, v188
	v_rcp_f32_e32 v190, v190
	s_waitcnt lgkmcnt(0)
	v_add_f32_e32 v188, v188, v189
	v_max_f32_e32 v188, 0xda24260, v188
	v_div_scale_f32 v206, s[44:45], v188, v188, v190
	v_rcp_f32_e32 v207, v206
	s_nop 0
	v_fma_f32 v208, -v206, v207, 1.0
	v_fmac_f32_e32 v207, v208, v207
	v_div_scale_f32 v208, vcc, v190, v188, v190
	v_mul_f32_e32 v209, v208, v207
	v_fma_f32 v189, -v206, v209, v208
	v_fmac_f32_e32 v209, v189, v207
	v_fma_f32 v206, -v206, v209, v208
	v_div_fmas_f32 v206, v206, v207, v209
	v_div_fixup_f32 v191, v206, v188, v190
	v_lshlrev_b32_e32 v210, 16, v139
	v_and_b32_e32 v211, 0xffff0000, v139
	v_fmac_f32_e32 v210, v6, v191
	v_fmac_f32_e32 v211, v7, v191
	v_cvt_pk_bf16_f32 v139, v210, v211
	v_lshlrev_b32_e32 v210, 16, v138
	v_and_b32_e32 v211, 0xffff0000, v138
	v_fmac_f32_e32 v210, v8, v191
	v_fmac_f32_e32 v211, v9, v191
	v_cvt_pk_bf16_f32 v138, v210, v211
	v_lshlrev_b32_e32 v210, 16, v137
	v_and_b32_e32 v211, 0xffff0000, v137
	v_fmac_f32_e32 v210, v14, v191
	v_fmac_f32_e32 v211, v15, v191
	v_cvt_pk_bf16_f32 v137, v210, v211
	v_lshlrev_b32_e32 v210, 16, v136
	v_and_b32_e32 v211, 0xffff0000, v136
	v_fmac_f32_e32 v210, v16, v191
	v_fmac_f32_e32 v211, v17, v191
	v_cvt_pk_bf16_f32 v136, v210, v211
	v_lshlrev_b32_e32 v210, 16, v123
	v_and_b32_e32 v211, 0xffff0000, v123
	v_fmac_f32_e32 v210, v22, v191
	v_fmac_f32_e32 v211, v23, v191
	v_cvt_pk_bf16_f32 v123, v210, v211
	v_lshlrev_b32_e32 v210, 16, v122
	v_and_b32_e32 v211, 0xffff0000, v122
	v_fmac_f32_e32 v210, v24, v191
	v_fmac_f32_e32 v211, v25, v191
	v_cvt_pk_bf16_f32 v122, v210, v211
	v_lshlrev_b32_e32 v210, 16, v121
	v_and_b32_e32 v211, 0xffff0000, v121
	v_fmac_f32_e32 v210, v30, v191
	v_fmac_f32_e32 v211, v31, v191
	v_cvt_pk_bf16_f32 v121, v210, v211
	v_lshlrev_b32_e32 v210, 16, v120
	v_and_b32_e32 v211, 0xffff0000, v120
	v_fmac_f32_e32 v210, v32, v191
	v_fmac_f32_e32 v211, v33, v191
	v_cvt_pk_bf16_f32 v120, v210, v211
	v_mov_b32_e32 v188, v147
	v_mov_b32_e32 v189, v146
	global_store_dwordx2 v184, v[188:189], s[38:39]
	s_nop 1
	v_mov_b32_e32 v188, v145
	v_mov_b32_e32 v189, v144
	global_store_dwordx2 v184, v[188:189], s[38:39] offset:32
	s_nop 1
	v_mov_b32_e32 v188, v143
	v_mov_b32_e32 v189, v142
	global_store_dwordx2 v184, v[188:189], s[38:39] offset:64
	s_nop 1
	v_mov_b32_e32 v188, v141
	v_mov_b32_e32 v189, v140
	global_store_dwordx2 v184, v[188:189], s[38:39] offset:96
	s_nop 1
	v_mov_b32_e32 v188, v139
	v_mov_b32_e32 v189, v138
	global_store_dwordx2 v185, v[188:189], s[38:39]
	s_nop 1
	v_mov_b32_e32 v188, v137
	v_mov_b32_e32 v189, v136
	global_store_dwordx2 v185, v[188:189], s[38:39] offset:32
	s_nop 1
	v_mov_b32_e32 v188, v123
	v_mov_b32_e32 v189, v122
	global_store_dwordx2 v185, v[188:189], s[38:39] offset:64
	s_nop 1
	v_mov_b32_e32 v188, v121
	v_mov_b32_e32 v189, v120
	global_store_dwordx2 v185, v[188:189], s[38:39] offset:96
	s_nop 1
	v_readlane_b32 s76, v236, 29
	v_readlane_b32 s77, v236, 30
	v_readlane_b32 s78, v236, 31
	v_readlane_b32 s79, v236, 32
	v_readlane_b32 s80, v236, 33
	v_readlane_b32 s81, v236, 34
	v_readlane_b32 s82, v236, 35
	v_readlane_b32 s83, v236, 36
	v_readlane_b32 s84, v236, 37
	v_readlane_b32 s85, v236, 38
	v_readlane_b32 s86, v236, 39
	v_readlane_b32 s87, v236, 40
	v_readlane_b32 s88, v236, 41
	v_readlane_b32 s89, v236, 42
	v_readlane_b32 s90, v236, 43
	v_readlane_b32 s91, v236, 44
	v_readlane_b32 s44, v236, 13
	v_readlane_b32 s45, v236, 14
	v_readlane_b32 s46, v236, 15
	v_readlane_b32 s47, v236, 16
	v_readlane_b32 s48, v236, 17
	v_readlane_b32 s49, v236, 18
	v_readlane_b32 s50, v236, 19
	v_readlane_b32 s51, v236, 20
	v_readlane_b32 s52, v236, 21
	v_readlane_b32 s53, v236, 22
	v_readlane_b32 s54, v236, 23
	v_readlane_b32 s55, v236, 24
	v_readlane_b32 s56, v236, 25
	v_readlane_b32 s57, v236, 26
	v_readlane_b32 s58, v236, 27
	v_readlane_b32 s59, v236, 28
	v_readlane_b32 s34, v236, 45
	v_readlane_b32 s35, v236, 46
	s_movk_i32 s33, 0x70
	s_movk_i32 s36, 0x3ff
	s_movk_i32 s38, 0x1680
	s_movk_i32 s43, 0x880
	s_movk_i32 s92, 0x480
	s_movk_i32 s93, 0x3300
	s_movk_i32 s94, 0x2080
	s_movk_i32 s95, 0x3000
	s_mov_b32 s37, 0x5a000
	s_mov_b32 s39, 0x2d000
	s_mov_b32 s42, 0x87000
	s_mov_b64 s[0:1], 0
	s_branch .LBB0_143
